# mod_item GEMV k-loop: 16 weight loads in flight, re-issued one iteration ahead, instead of one load + vmcnt(0) per k; on top of v98
# speedup vs baseline: 1.0109x; 1.0036x over previous
.LBB0_67:
	s_or_b64 exec, exec, s[4:5]
	s_mov_b32 s0, 0x2aaaaaab
	v_mul_hi_i32 v2, v4, s0
	v_lshrrev_b32_e32 v3, 31, v2
	v_ashrrev_i32_e32 v2, 4, v2
	v_add_u32_e32 v41, v2, v3
	s_movk_i32 s0, 0x60
	v_mul_lo_u32 v2, v41, s0
	v_sub_u32_e32 v2, v4, v2
	v_ashrrev_i32_e32 v59, 6, v40
	v_lshlrev_b32_e32 v42, 6, v2
	v_lshlrev_b32_e32 v2, 8, v59
	v_mad_i64_i32 v[2:3], s[0:1], v2, s52, 0
	s_mov_b32 s0, 0x1800000
	v_ashrrev_i32_e32 v43, 31, v42
	v_mad_i64_i32 v[2:3], s[0:1], v41, s0, v[2:3]
	v_and_b32_e32 v38, 63, v40
	v_lshl_add_u64 v[2:3], v[42:43], 2, v[2:3]
	v_lshl_or_b32 v2, v38, 2, v2
	v_mov_b32_e32 v10, 0
	v_lshl_add_u64 v[44:45], s[60:61], 0, v[2:3]
	v_lshl_add_u32 v60, v59, 10, v194
	s_mov_b64 s[0:1], 0
	v_mov_b32_e32 v11, v10
	v_mov_b32_e32 v18, v10
	v_mov_b32_e32 v19, v10
	v_mov_b32_e32 v26, v10
	v_mov_b32_e32 v27, v10
	v_mov_b32_e32 v34, v10
	v_mov_b32_e32 v35, v10
	v_mov_b32_e32 v61, v10
	s_waitcnt lgkmcnt(0)
	s_barrier
	v_lshl_add_u64 v[46:47], v[44:45], 0, s[0:1]
	s_mov_b64 s[4:5], 0x6000
	global_load_dword v98, v[46:47], off
	v_lshl_add_u64 v[46:47], v[46:47], 0, s[4:5]
	global_load_dword v99, v[46:47], off
	v_lshl_add_u64 v[46:47], v[46:47], 0, s[4:5]
	global_load_dword v100, v[46:47], off
	v_lshl_add_u64 v[46:47], v[46:47], 0, s[4:5]
	global_load_dword v101, v[46:47], off
	v_lshl_add_u64 v[46:47], v[46:47], 0, s[4:5]
	global_load_dword v102, v[46:47], off
	v_lshl_add_u64 v[46:47], v[46:47], 0, s[4:5]
	global_load_dword v103, v[46:47], off
	v_lshl_add_u64 v[46:47], v[46:47], 0, s[4:5]
	global_load_dword v104, v[46:47], off
	v_lshl_add_u64 v[46:47], v[46:47], 0, s[4:5]
	global_load_dword v105, v[46:47], off
	v_lshl_add_u64 v[46:47], v[46:47], 0, s[4:5]
	global_load_dword v106, v[46:47], off
	v_lshl_add_u64 v[46:47], v[46:47], 0, s[4:5]
	global_load_dword v107, v[46:47], off
	v_lshl_add_u64 v[46:47], v[46:47], 0, s[4:5]
	global_load_dword v108, v[46:47], off
	v_lshl_add_u64 v[46:47], v[46:47], 0, s[4:5]
	global_load_dword v109, v[46:47], off
	v_lshl_add_u64 v[46:47], v[46:47], 0, s[4:5]
	global_load_dword v110, v[46:47], off
	v_lshl_add_u64 v[46:47], v[46:47], 0, s[4:5]
	global_load_dword v111, v[46:47], off
	v_lshl_add_u64 v[46:47], v[46:47], 0, s[4:5]
	global_load_dword v112, v[46:47], off
	v_lshl_add_u64 v[46:47], v[46:47], 0, s[4:5]
	global_load_dword v113, v[46:47], off
	v_lshl_add_u64 v[46:47], v[46:47], 0, s[4:5]
	s_mov_b32 s0, 0
.Lmod_k:
	ds_read_b128 v[114:117], v60
	ds_read_b128 v[118:121], v60 offset:4096
	ds_read_b128 v[122:125], v60 offset:8192
	ds_read_b128 v[126:129], v60 offset:12288
	ds_read_b128 v[130:133], v60 offset:16384
	ds_read_b128 v[134:137], v60 offset:20480
	ds_read_b128 v[138:141], v60 offset:24576
	ds_read_b128 v[142:145], v60 offset:28672
	ds_read_b128 v[146:149], v60 offset:32768
	s_waitcnt vmcnt(12)
	s_waitcnt lgkmcnt(0)
	v_fmac_f32_e32 v10, v98, v114
	v_fmac_f32_e32 v11, v98, v118
	v_fmac_f32_e32 v18, v98, v122
	v_fmac_f32_e32 v19, v98, v126
	v_fmac_f32_e32 v26, v98, v130
	v_fmac_f32_e32 v27, v98, v134
	v_fmac_f32_e32 v34, v98, v138
	v_fmac_f32_e32 v35, v98, v142
	v_fmac_f32_e32 v61, v98, v146
	v_fmac_f32_e32 v10, v99, v115
	v_fmac_f32_e32 v11, v99, v119
	v_fmac_f32_e32 v18, v99, v123
	v_fmac_f32_e32 v19, v99, v127
	v_fmac_f32_e32 v26, v99, v131
	v_fmac_f32_e32 v27, v99, v135
	v_fmac_f32_e32 v34, v99, v139
	v_fmac_f32_e32 v35, v99, v143
	v_fmac_f32_e32 v61, v99, v147
	v_fmac_f32_e32 v10, v100, v116
	v_fmac_f32_e32 v11, v100, v120
	v_fmac_f32_e32 v18, v100, v124
	v_fmac_f32_e32 v19, v100, v128
	v_fmac_f32_e32 v26, v100, v132
	v_fmac_f32_e32 v27, v100, v136
	v_fmac_f32_e32 v34, v100, v140
	v_fmac_f32_e32 v35, v100, v144
	v_fmac_f32_e32 v61, v100, v148
	v_fmac_f32_e32 v10, v101, v117
	v_fmac_f32_e32 v11, v101, v121
	v_fmac_f32_e32 v18, v101, v125
	v_fmac_f32_e32 v19, v101, v129
	v_fmac_f32_e32 v26, v101, v133
	v_fmac_f32_e32 v27, v101, v137
	v_fmac_f32_e32 v34, v101, v141
	v_fmac_f32_e32 v35, v101, v145
	v_fmac_f32_e32 v61, v101, v149
	global_load_dword v98, v[46:47], off
	v_lshl_add_u64 v[46:47], v[46:47], 0, s[4:5]
	global_load_dword v99, v[46:47], off
	v_lshl_add_u64 v[46:47], v[46:47], 0, s[4:5]
	global_load_dword v100, v[46:47], off
	v_lshl_add_u64 v[46:47], v[46:47], 0, s[4:5]
	global_load_dword v101, v[46:47], off
	v_lshl_add_u64 v[46:47], v[46:47], 0, s[4:5]
	ds_read_b128 v[114:117], v60 offset:16
	ds_read_b128 v[118:121], v60 offset:4112
	ds_read_b128 v[122:125], v60 offset:8208
	ds_read_b128 v[126:129], v60 offset:12304
	ds_read_b128 v[130:133], v60 offset:16400
	ds_read_b128 v[134:137], v60 offset:20496
	ds_read_b128 v[138:141], v60 offset:24592
	ds_read_b128 v[142:145], v60 offset:28688
	ds_read_b128 v[146:149], v60 offset:32784
	s_waitcnt vmcnt(12)
	s_waitcnt lgkmcnt(0)
	v_fmac_f32_e32 v10, v102, v114
	v_fmac_f32_e32 v11, v102, v118
	v_fmac_f32_e32 v18, v102, v122
	v_fmac_f32_e32 v19, v102, v126
	v_fmac_f32_e32 v26, v102, v130
	v_fmac_f32_e32 v27, v102, v134
	v_fmac_f32_e32 v34, v102, v138
	v_fmac_f32_e32 v35, v102, v142
	v_fmac_f32_e32 v61, v102, v146
	v_fmac_f32_e32 v10, v103, v115
	v_fmac_f32_e32 v11, v103, v119
	v_fmac_f32_e32 v18, v103, v123
	v_fmac_f32_e32 v19, v103, v127
	v_fmac_f32_e32 v26, v103, v131
	v_fmac_f32_e32 v27, v103, v135
	v_fmac_f32_e32 v34, v103, v139
	v_fmac_f32_e32 v35, v103, v143
	v_fmac_f32_e32 v61, v103, v147
	v_fmac_f32_e32 v10, v104, v116
	v_fmac_f32_e32 v11, v104, v120
	v_fmac_f32_e32 v18, v104, v124
	v_fmac_f32_e32 v19, v104, v128
	v_fmac_f32_e32 v26, v104, v132
	v_fmac_f32_e32 v27, v104, v136
	v_fmac_f32_e32 v34, v104, v140
	v_fmac_f32_e32 v35, v104, v144
	v_fmac_f32_e32 v61, v104, v148
	v_fmac_f32_e32 v10, v105, v117
	v_fmac_f32_e32 v11, v105, v121
	v_fmac_f32_e32 v18, v105, v125
	v_fmac_f32_e32 v19, v105, v129
	v_fmac_f32_e32 v26, v105, v133
	v_fmac_f32_e32 v27, v105, v137
	v_fmac_f32_e32 v34, v105, v141
	v_fmac_f32_e32 v35, v105, v145
	v_fmac_f32_e32 v61, v105, v149
	global_load_dword v102, v[46:47], off
	v_lshl_add_u64 v[46:47], v[46:47], 0, s[4:5]
	global_load_dword v103, v[46:47], off
	v_lshl_add_u64 v[46:47], v[46:47], 0, s[4:5]
	global_load_dword v104, v[46:47], off
	v_lshl_add_u64 v[46:47], v[46:47], 0, s[4:5]
	global_load_dword v105, v[46:47], off
	v_lshl_add_u64 v[46:47], v[46:47], 0, s[4:5]
	ds_read_b128 v[114:117], v60 offset:32
	ds_read_b128 v[118:121], v60 offset:4128
	ds_read_b128 v[122:125], v60 offset:8224
	ds_read_b128 v[126:129], v60 offset:12320
	ds_read_b128 v[130:133], v60 offset:16416
	ds_read_b128 v[134:137], v60 offset:20512
	ds_read_b128 v[138:141], v60 offset:24608
	ds_read_b128 v[142:145], v60 offset:28704
	ds_read_b128 v[146:149], v60 offset:32800
	s_waitcnt vmcnt(12)
	s_waitcnt lgkmcnt(0)
	v_fmac_f32_e32 v10, v106, v114
	v_fmac_f32_e32 v11, v106, v118
	v_fmac_f32_e32 v18, v106, v122
	v_fmac_f32_e32 v19, v106, v126
	v_fmac_f32_e32 v26, v106, v130
	v_fmac_f32_e32 v27, v106, v134
	v_fmac_f32_e32 v34, v106, v138
	v_fmac_f32_e32 v35, v106, v142
	v_fmac_f32_e32 v61, v106, v146
	v_fmac_f32_e32 v10, v107, v115
	v_fmac_f32_e32 v11, v107, v119
	v_fmac_f32_e32 v18, v107, v123
	v_fmac_f32_e32 v19, v107, v127
	v_fmac_f32_e32 v26, v107, v131
	v_fmac_f32_e32 v27, v107, v135
	v_fmac_f32_e32 v34, v107, v139
	v_fmac_f32_e32 v35, v107, v143
	v_fmac_f32_e32 v61, v107, v147
	v_fmac_f32_e32 v10, v108, v116
	v_fmac_f32_e32 v11, v108, v120
	v_fmac_f32_e32 v18, v108, v124
	v_fmac_f32_e32 v19, v108, v128
	v_fmac_f32_e32 v26, v108, v132
	v_fmac_f32_e32 v27, v108, v136
	v_fmac_f32_e32 v34, v108, v140
	v_fmac_f32_e32 v35, v108, v144
	v_fmac_f32_e32 v61, v108, v148
	v_fmac_f32_e32 v10, v109, v117
	v_fmac_f32_e32 v11, v109, v121
	v_fmac_f32_e32 v18, v109, v125
	v_fmac_f32_e32 v19, v109, v129
	v_fmac_f32_e32 v26, v109, v133
	v_fmac_f32_e32 v27, v109, v137
	v_fmac_f32_e32 v34, v109, v141
	v_fmac_f32_e32 v35, v109, v145
	v_fmac_f32_e32 v61, v109, v149
	global_load_dword v106, v[46:47], off
	v_lshl_add_u64 v[46:47], v[46:47], 0, s[4:5]
	global_load_dword v107, v[46:47], off
	v_lshl_add_u64 v[46:47], v[46:47], 0, s[4:5]
	global_load_dword v108, v[46:47], off
	v_lshl_add_u64 v[46:47], v[46:47], 0, s[4:5]
	global_load_dword v109, v[46:47], off
	v_lshl_add_u64 v[46:47], v[46:47], 0, s[4:5]
	ds_read_b128 v[114:117], v60 offset:48
	ds_read_b128 v[118:121], v60 offset:4144
	ds_read_b128 v[122:125], v60 offset:8240
	ds_read_b128 v[126:129], v60 offset:12336
	ds_read_b128 v[130:133], v60 offset:16432
	ds_read_b128 v[134:137], v60 offset:20528
	ds_read_b128 v[138:141], v60 offset:24624
	ds_read_b128 v[142:145], v60 offset:28720
	ds_read_b128 v[146:149], v60 offset:32816
	s_waitcnt vmcnt(12)
	s_waitcnt lgkmcnt(0)
	v_fmac_f32_e32 v10, v110, v114
	v_fmac_f32_e32 v11, v110, v118
	v_fmac_f32_e32 v18, v110, v122
	v_fmac_f32_e32 v19, v110, v126
	v_fmac_f32_e32 v26, v110, v130
	v_fmac_f32_e32 v27, v110, v134
	v_fmac_f32_e32 v34, v110, v138
	v_fmac_f32_e32 v35, v110, v142
	v_fmac_f32_e32 v61, v110, v146
	v_fmac_f32_e32 v10, v111, v115
	v_fmac_f32_e32 v11, v111, v119
	v_fmac_f32_e32 v18, v111, v123
	v_fmac_f32_e32 v19, v111, v127
	v_fmac_f32_e32 v26, v111, v131
	v_fmac_f32_e32 v27, v111, v135
	v_fmac_f32_e32 v34, v111, v139
	v_fmac_f32_e32 v35, v111, v143
	v_fmac_f32_e32 v61, v111, v147
	v_fmac_f32_e32 v10, v112, v116
	v_fmac_f32_e32 v11, v112, v120
	v_fmac_f32_e32 v18, v112, v124
	v_fmac_f32_e32 v19, v112, v128
	v_fmac_f32_e32 v26, v112, v132
	v_fmac_f32_e32 v27, v112, v136
	v_fmac_f32_e32 v34, v112, v140
	v_fmac_f32_e32 v35, v112, v144
	v_fmac_f32_e32 v61, v112, v148
	v_fmac_f32_e32 v10, v113, v117
	v_fmac_f32_e32 v11, v113, v121
	v_fmac_f32_e32 v18, v113, v125
	v_fmac_f32_e32 v19, v113, v129
	v_fmac_f32_e32 v26, v113, v133
	v_fmac_f32_e32 v27, v113, v137
	v_fmac_f32_e32 v34, v113, v141
	v_fmac_f32_e32 v35, v113, v145
	v_fmac_f32_e32 v61, v113, v149
	global_load_dword v110, v[46:47], off
	v_lshl_add_u64 v[46:47], v[46:47], 0, s[4:5]
	global_load_dword v111, v[46:47], off
	v_lshl_add_u64 v[46:47], v[46:47], 0, s[4:5]
	global_load_dword v112, v[46:47], off
	v_lshl_add_u64 v[46:47], v[46:47], 0, s[4:5]
	global_load_dword v113, v[46:47], off
	v_lshl_add_u64 v[46:47], v[46:47], 0, s[4:5]
	v_add_u32_e32 v60, 64, v60
	s_add_i32 s0, s0, 1
	s_cmp_lg_u32 s0, 15
	s_cbranch_scc1 .Lmod_k
	ds_read_b128 v[114:117], v60
	ds_read_b128 v[118:121], v60 offset:4096
	ds_read_b128 v[122:125], v60 offset:8192
	ds_read_b128 v[126:129], v60 offset:12288
	ds_read_b128 v[130:133], v60 offset:16384
	ds_read_b128 v[134:137], v60 offset:20480
	ds_read_b128 v[138:141], v60 offset:24576
	ds_read_b128 v[142:145], v60 offset:28672
	ds_read_b128 v[146:149], v60 offset:32768
	s_waitcnt vmcnt(12)
	s_waitcnt lgkmcnt(0)
	v_fmac_f32_e32 v10, v98, v114
	v_fmac_f32_e32 v11, v98, v118
	v_fmac_f32_e32 v18, v98, v122
	v_fmac_f32_e32 v19, v98, v126
	v_fmac_f32_e32 v26, v98, v130
	v_fmac_f32_e32 v27, v98, v134
	v_fmac_f32_e32 v34, v98, v138
	v_fmac_f32_e32 v35, v98, v142
	v_fmac_f32_e32 v61, v98, v146
	v_fmac_f32_e32 v10, v99, v115
	v_fmac_f32_e32 v11, v99, v119
	v_fmac_f32_e32 v18, v99, v123
	v_fmac_f32_e32 v19, v99, v127
	v_fmac_f32_e32 v26, v99, v131
	v_fmac_f32_e32 v27, v99, v135
	v_fmac_f32_e32 v34, v99, v139
	v_fmac_f32_e32 v35, v99, v143
	v_fmac_f32_e32 v61, v99, v147
	v_fmac_f32_e32 v10, v100, v116
	v_fmac_f32_e32 v11, v100, v120
	v_fmac_f32_e32 v18, v100, v124
	v_fmac_f32_e32 v19, v100, v128
	v_fmac_f32_e32 v26, v100, v132
	v_fmac_f32_e32 v27, v100, v136
	v_fmac_f32_e32 v34, v100, v140
	v_fmac_f32_e32 v35, v100, v144
	v_fmac_f32_e32 v61, v100, v148
	v_fmac_f32_e32 v10, v101, v117
	v_fmac_f32_e32 v11, v101, v121
	v_fmac_f32_e32 v18, v101, v125
	v_fmac_f32_e32 v19, v101, v129
	v_fmac_f32_e32 v26, v101, v133
	v_fmac_f32_e32 v27, v101, v137
	v_fmac_f32_e32 v34, v101, v141
	v_fmac_f32_e32 v35, v101, v145
	v_fmac_f32_e32 v61, v101, v149
	ds_read_b128 v[114:117], v60 offset:16
	ds_read_b128 v[118:121], v60 offset:4112
	ds_read_b128 v[122:125], v60 offset:8208
	ds_read_b128 v[126:129], v60 offset:12304
	ds_read_b128 v[130:133], v60 offset:16400
	ds_read_b128 v[134:137], v60 offset:20496
	ds_read_b128 v[138:141], v60 offset:24592
	ds_read_b128 v[142:145], v60 offset:28688
	ds_read_b128 v[146:149], v60 offset:32784
	s_waitcnt vmcnt(8)
	s_waitcnt lgkmcnt(0)
	v_fmac_f32_e32 v10, v102, v114
	v_fmac_f32_e32 v11, v102, v118
	v_fmac_f32_e32 v18, v102, v122
	v_fmac_f32_e32 v19, v102, v126
	v_fmac_f32_e32 v26, v102, v130
	v_fmac_f32_e32 v27, v102, v134
	v_fmac_f32_e32 v34, v102, v138
	v_fmac_f32_e32 v35, v102, v142
	v_fmac_f32_e32 v61, v102, v146
	v_fmac_f32_e32 v10, v103, v115
	v_fmac_f32_e32 v11, v103, v119
	v_fmac_f32_e32 v18, v103, v123
	v_fmac_f32_e32 v19, v103, v127
	v_fmac_f32_e32 v26, v103, v131
	v_fmac_f32_e32 v27, v103, v135
	v_fmac_f32_e32 v34, v103, v139
	v_fmac_f32_e32 v35, v103, v143
	v_fmac_f32_e32 v61, v103, v147
	v_fmac_f32_e32 v10, v104, v116
	v_fmac_f32_e32 v11, v104, v120
	v_fmac_f32_e32 v18, v104, v124
	v_fmac_f32_e32 v19, v104, v128
	v_fmac_f32_e32 v26, v104, v132
	v_fmac_f32_e32 v27, v104, v136
	v_fmac_f32_e32 v34, v104, v140
	v_fmac_f32_e32 v35, v104, v144
	v_fmac_f32_e32 v61, v104, v148
	v_fmac_f32_e32 v10, v105, v117
	v_fmac_f32_e32 v11, v105, v121
	v_fmac_f32_e32 v18, v105, v125
	v_fmac_f32_e32 v19, v105, v129
	v_fmac_f32_e32 v26, v105, v133
	v_fmac_f32_e32 v27, v105, v137
	v_fmac_f32_e32 v34, v105, v141
	v_fmac_f32_e32 v35, v105, v145
	v_fmac_f32_e32 v61, v105, v149
	ds_read_b128 v[114:117], v60 offset:32
	ds_read_b128 v[118:121], v60 offset:4128
	ds_read_b128 v[122:125], v60 offset:8224
	ds_read_b128 v[126:129], v60 offset:12320
	ds_read_b128 v[130:133], v60 offset:16416
	ds_read_b128 v[134:137], v60 offset:20512
	ds_read_b128 v[138:141], v60 offset:24608
	ds_read_b128 v[142:145], v60 offset:28704
	ds_read_b128 v[146:149], v60 offset:32800
	s_waitcnt vmcnt(4)
	s_waitcnt lgkmcnt(0)
	v_fmac_f32_e32 v10, v106, v114
	v_fmac_f32_e32 v11, v106, v118
	v_fmac_f32_e32 v18, v106, v122
	v_fmac_f32_e32 v19, v106, v126
	v_fmac_f32_e32 v26, v106, v130
	v_fmac_f32_e32 v27, v106, v134
	v_fmac_f32_e32 v34, v106, v138
	v_fmac_f32_e32 v35, v106, v142
	v_fmac_f32_e32 v61, v106, v146
	v_fmac_f32_e32 v10, v107, v115
	v_fmac_f32_e32 v11, v107, v119
	v_fmac_f32_e32 v18, v107, v123
	v_fmac_f32_e32 v19, v107, v127
	v_fmac_f32_e32 v26, v107, v131
	v_fmac_f32_e32 v27, v107, v135
	v_fmac_f32_e32 v34, v107, v139
	v_fmac_f32_e32 v35, v107, v143
	v_fmac_f32_e32 v61, v107, v147
	v_fmac_f32_e32 v10, v108, v116
	v_fmac_f32_e32 v11, v108, v120
	v_fmac_f32_e32 v18, v108, v124
	v_fmac_f32_e32 v19, v108, v128
	v_fmac_f32_e32 v26, v108, v132
	v_fmac_f32_e32 v27, v108, v136
	v_fmac_f32_e32 v34, v108, v140
	v_fmac_f32_e32 v35, v108, v144
	v_fmac_f32_e32 v61, v108, v148
	v_fmac_f32_e32 v10, v109, v117
	v_fmac_f32_e32 v11, v109, v121
	v_fmac_f32_e32 v18, v109, v125
	v_fmac_f32_e32 v19, v109, v129
	v_fmac_f32_e32 v26, v109, v133
	v_fmac_f32_e32 v27, v109, v137
	v_fmac_f32_e32 v34, v109, v141
	v_fmac_f32_e32 v35, v109, v145
	v_fmac_f32_e32 v61, v109, v149
	ds_read_b128 v[114:117], v60 offset:48
	ds_read_b128 v[118:121], v60 offset:4144
	ds_read_b128 v[122:125], v60 offset:8240
	ds_read_b128 v[126:129], v60 offset:12336
	ds_read_b128 v[130:133], v60 offset:16432
	ds_read_b128 v[134:137], v60 offset:20528
	ds_read_b128 v[138:141], v60 offset:24624
	ds_read_b128 v[142:145], v60 offset:28720
	ds_read_b128 v[146:149], v60 offset:32816
	s_waitcnt vmcnt(0)
	s_waitcnt lgkmcnt(0)
	v_fmac_f32_e32 v10, v110, v114
	v_fmac_f32_e32 v11, v110, v118
	v_fmac_f32_e32 v18, v110, v122
	v_fmac_f32_e32 v19, v110, v126
	v_fmac_f32_e32 v26, v110, v130
	v_fmac_f32_e32 v27, v110, v134
	v_fmac_f32_e32 v34, v110, v138
	v_fmac_f32_e32 v35, v110, v142
	v_fmac_f32_e32 v61, v110, v146
	v_fmac_f32_e32 v10, v111, v115
	v_fmac_f32_e32 v11, v111, v119
	v_fmac_f32_e32 v18, v111, v123
	v_fmac_f32_e32 v19, v111, v127
	v_fmac_f32_e32 v26, v111, v131
	v_fmac_f32_e32 v27, v111, v135
	v_fmac_f32_e32 v34, v111, v139
	v_fmac_f32_e32 v35, v111, v143
	v_fmac_f32_e32 v61, v111, v147
	v_fmac_f32_e32 v10, v112, v116
	v_fmac_f32_e32 v11, v112, v120
	v_fmac_f32_e32 v18, v112, v124
	v_fmac_f32_e32 v19, v112, v128
	v_fmac_f32_e32 v26, v112, v132
	v_fmac_f32_e32 v27, v112, v136
	v_fmac_f32_e32 v34, v112, v140
	v_fmac_f32_e32 v35, v112, v144
	v_fmac_f32_e32 v61, v112, v148
	v_fmac_f32_e32 v10, v113, v117
	v_fmac_f32_e32 v11, v113, v121
	v_fmac_f32_e32 v18, v113, v125
	v_fmac_f32_e32 v19, v113, v129
	v_fmac_f32_e32 v26, v113, v133
	v_fmac_f32_e32 v27, v113, v137
	v_fmac_f32_e32 v34, v113, v141
	v_fmac_f32_e32 v35, v113, v145
	v_fmac_f32_e32 v61, v113, v149
	s_movk_i32 s0, 0x900
	v_mul_lo_u32 v2, v59, s0
	v_lshlrev_b32_e32 v38, 2, v38
	v_add3_u32 v2, v194, v2, v38
	v_cmp_gt_u32_e32 vcc, 64, v40
	ds_write2st64_b32 v2, v10, v11 offset0:144 offset1:145
	ds_write2st64_b32 v2, v18, v19 offset0:146 offset1:147
	ds_write2st64_b32 v2, v26, v27 offset0:148 offset1:149
	ds_write2st64_b32 v2, v34, v35 offset0:150 offset1:151
	ds_write_b32 v2, v61 offset:38912
	s_waitcnt lgkmcnt(0)
	s_barrier
	s_and_saveexec_b64 s[0:1], vcc
	s_cbranch_execz .LBB0_4
	v_lshl_add_u32 v11, v40, 2, v194
	ds_read2st64_b32 v[12:13], v11 offset0:144 offset1:145
	ds_read2st64_b32 v[6:7], v11 offset0:152 offset1:153
	ds_read2st64_b32 v[14:15], v11 offset0:162 offset1:163
	ds_read2st64_b32 v[8:9], v11 offset0:170 offset1:171
	s_movk_i32 s4, 0x1800
	v_mad_u64_u32 v[2:3], s[4:5], v41, s4, v[42:43]
	v_or_b32_e32 v2, v40, v2
	v_ashrrev_i32_e32 v3, 31, v2
	s_waitcnt lgkmcnt(2)
	v_add_f32_e32 v7, v12, v7
	v_lshl_add_u64 v[4:5], v[2:3], 2, s[62:63]
	s_waitcnt lgkmcnt(1)
	v_add_f32_e32 v7, v7, v14
	s_waitcnt lgkmcnt(0)
	v_add_f32_e32 v7, v7, v9
	global_load_dword v9, v[4:5], off
	v_lshl_add_u64 v[2:3], v[42:43], 2, s[28:29]
	v_lshl_add_u32 v10, v41, 3, v41
	v_lshl_add_u64 v[2:3], v[2:3], 0, v[38:39]
	v_mad_i64_i32 v[16:17], s[4:5], v10, s52, v[2:3]
	s_waitcnt vmcnt(0)
	v_add_f32_e32 v7, v7, v9
	global_store_dword v[16:17], v7, off
	global_load_dword v9, v[4:5], off
	ds_read2st64_b32 v[16:17], v11 offset0:154 offset1:155
	s_waitcnt lgkmcnt(0)
	v_add_f32_e32 v7, v13, v16
	ds_read2st64_b32 v[12:13], v11 offset0:172 offset1:173
	v_add_f32_e32 v7, v7, v15
	s_waitcnt lgkmcnt(0)
	v_add_f32_e32 v7, v7, v12
	s_waitcnt vmcnt(0)
	v_add_f32_e32 v7, v7, v9
	v_add_u32_e32 v9, 1, v10
	v_mad_i64_i32 v[14:15], s[4:5], v9, s52, v[2:3]
	global_store_dword v[14:15], v7, off
	global_load_dword v9, v[4:5], off
	ds_read2st64_b32 v[14:15], v11 offset0:146 offset1:147
	s_waitcnt lgkmcnt(0)
	v_add_f32_e32 v7, v14, v17
	ds_read2st64_b32 v[16:17], v11 offset0:164 offset1:165
	s_waitcnt lgkmcnt(0)
	v_add_f32_e32 v7, v7, v16
	v_add_f32_e32 v7, v7, v13
	s_waitcnt vmcnt(0)
	v_add_f32_e32 v7, v7, v9
	v_add_u32_e32 v9, 2, v10
	v_mad_i64_i32 v[12:13], s[4:5], v9, s52, v[2:3]
	global_store_dword v[12:13], v7, off
	global_load_dword v9, v[4:5], off
	ds_read2st64_b32 v[12:13], v11 offset0:156 offset1:157
	s_waitcnt lgkmcnt(0)
	v_add_f32_e32 v7, v15, v12
	ds_read2st64_b32 v[14:15], v11 offset0:174 offset1:175
	v_add_f32_e32 v7, v7, v17
	s_waitcnt lgkmcnt(0)
	v_add_f32_e32 v7, v7, v14
	s_waitcnt vmcnt(0)
	v_add_f32_e32 v7, v7, v9
	v_add_u32_e32 v9, 3, v10
	v_mad_i64_i32 v[16:17], s[4:5], v9, s52, v[2:3]
	global_store_dword v[16:17], v7, off
	global_load_dword v9, v[4:5], off
	ds_read2st64_b32 v[16:17], v11 offset0:148 offset1:149
	s_waitcnt lgkmcnt(0)
	v_add_f32_e32 v7, v16, v13
	ds_read2st64_b32 v[12:13], v11 offset0:166 offset1:167
	s_waitcnt lgkmcnt(0)
	v_add_f32_e32 v7, v7, v12
	v_add_f32_e32 v7, v7, v15
	s_waitcnt vmcnt(0)
	v_add_f32_e32 v7, v7, v9
	v_add_u32_e32 v9, 4, v10
	v_mad_i64_i32 v[14:15], s[4:5], v9, s52, v[2:3]
	global_store_dword v[14:15], v7, off
	global_load_dword v9, v[4:5], off
	ds_read2st64_b32 v[14:15], v11 offset0:158 offset1:159
	s_waitcnt lgkmcnt(0)
	v_add_f32_e32 v7, v17, v14
	v_add_f32_e32 v7, v7, v13
	ds_read2st64_b32 v[12:13], v11 offset0:176 offset1:177
	s_waitcnt lgkmcnt(0)
	v_add_f32_e32 v7, v7, v12
	s_waitcnt vmcnt(0)
	v_add_f32_e32 v7, v7, v9
	v_add_u32_e32 v9, 5, v10
	v_mad_i64_i32 v[16:17], s[4:5], v9, s52, v[2:3]
	global_store_dword v[16:17], v7, off
	global_load_dword v9, v[4:5], off
	ds_read2st64_b32 v[16:17], v11 offset0:150 offset1:151
	s_waitcnt lgkmcnt(0)
	v_add_f32_e32 v7, v16, v15
	ds_read2st64_b32 v[14:15], v11 offset0:168 offset1:169
	s_waitcnt lgkmcnt(0)
	v_add_f32_e32 v7, v7, v14
	v_add_f32_e32 v7, v7, v13
	s_waitcnt vmcnt(0)
	v_add_f32_e32 v7, v7, v9
	v_add_u32_e32 v9, 6, v10
	v_mad_i64_i32 v[12:13], s[4:5], v9, s52, v[2:3]
	global_store_dword v[12:13], v7, off
	global_load_dword v9, v[4:5], off
	ds_read2st64_b32 v[12:13], v11 offset0:160 offset1:161
	s_waitcnt lgkmcnt(0)
	v_add_f32_e32 v7, v17, v12
	v_add_f32_e32 v7, v7, v15
	ds_read2st64_b32 v[14:15], v11 offset0:178 offset1:179
	v_add_f32_e32 v6, v6, v13
	v_add_f32_e32 v6, v6, v8
	s_waitcnt lgkmcnt(0)
	v_add_f32_e32 v7, v7, v14
	v_add_f32_e32 v6, v6, v15
	s_waitcnt vmcnt(0)
	v_add_f32_e32 v7, v7, v9
	v_add_u32_e32 v9, 7, v10
	v_mad_i64_i32 v[16:17], s[4:5], v9, s52, v[2:3]
	global_store_dword v[16:17], v7, off
	global_load_dword v4, v[4:5], off
	v_add_u32_e32 v5, 8, v10
	v_mad_i64_i32 v[2:3], s[4:5], v5, s52, v[2:3]
	s_waitcnt vmcnt(0)
	v_add_f32_e32 v4, v6, v4
	global_store_dword v[2:3], v4, off
	s_branch .LBB0_4
